# lin_C2 de-serialised + MoBA: prologue loads in flight, max3 chains for the past-block row max, permlane swaps instead of ds_bpermute reductions
# speedup vs baseline: 1.0171x; 1.0083x over previous
.LBB0_93:
	s_xor_b64 s[56:57], s[0:1], -1
	s_and_b64 s[0:1], s[0:1], exec
	s_cselect_b32 s8, s43, s44
	s_lshl_b32 s46, s8, 7
	s_ashr_i32 s1, s46, 31
	s_add_u32 s0, s46, s6
	s_addc_u32 s1, s1, 0
	v_lshl_add_u64 v[36:37], s[0:1], 0, v[116:117]
	v_mov_b64_e32 v[40:41], s[88:89]
	v_mad_u64_u32 v[38:39], s[10:11], v36, s72, v[40:41]
	v_mad_i32_i24 v39, v37, s72, v39
	s_lshl_b32 s20, s45, 1
	v_lshl_add_u64 v[36:37], v[38:39], 0, s[20:21]
	v_lshl_add_u64 v[36:37], v[36:37], 0, v[2:3]
	v_add_co_u32_e32 v36, vcc, s3, v36
	s_nop 1
	v_addc_co_u32_e32 v37, vcc, 0, v37, vcc
	global_load_dwordx4 v[4:7], v[36:37], off
	v_lshl_add_u64 v[36:37], s[0:1], 0, v[122:123]
	v_mad_u64_u32 v[38:39], s[10:11], v36, s72, v[40:41]
	v_mad_i32_i24 v39, v37, s72, v39
	v_lshl_add_u64 v[36:37], v[38:39], 0, s[20:21]
	v_lshl_add_u64 v[36:37], v[36:37], 0, v[2:3]
	v_add_co_u32_e32 v36, vcc, s3, v36
	s_nop 1
	v_addc_co_u32_e32 v37, vcc, 0, v37, vcc
	global_load_dwordx4 v[8:11], v[36:37], off
	v_lshl_add_u64 v[36:37], s[0:1], 0, v[124:125]
	v_mad_u64_u32 v[38:39], s[10:11], v36, s72, v[40:41]
	v_mad_i32_i24 v39, v37, s72, v39
	v_lshl_add_u64 v[36:37], v[38:39], 0, s[20:21]
	v_lshl_add_u64 v[36:37], v[36:37], 0, v[2:3]
	v_add_co_u32_e32 v36, vcc, s3, v36
	s_nop 1
	v_addc_co_u32_e32 v37, vcc, 0, v37, vcc
	global_load_dwordx4 v[12:15], v[36:37], off
	v_lshl_add_u64 v[36:37], s[0:1], 0, v[126:127]
	v_mad_u64_u32 v[38:39], s[0:1], v36, s72, v[40:41]
	v_mad_i32_i24 v39, v37, s72, v39
	v_lshl_add_u64 v[36:37], v[38:39], 0, s[20:21]
	v_lshl_add_u64 v[36:37], v[36:37], 0, v[2:3]
	v_add_co_u32_e32 v36, vcc, 0x1000, v36
	s_nop 1
	v_addc_co_u32_e32 v37, vcc, 0, v37, vcc
	global_load_dwordx4 v[16:19], v[36:37], off
	global_load_dwordx4 v[20:23], v[142:143], off
	global_load_dwordx4 v[24:27], v[144:145], off
	s_barrier
	v_add_u32_e32 v52, v133, v170
	v_mov_b32_e32 v44, v156
	v_mov_b32_e32 v45, v135
	v_mov_b32_e32 v40, 0
	s_mov_b32 s0, 16
	v_mov_b32_e32 v41, v40
	v_mov_b32_e32 v42, v40
	v_mov_b32_e32 v43, v40
	s_waitcnt vmcnt(5)
	ds_write_b128 v52, v[4:7]
	s_waitcnt vmcnt(4)
	ds_write_b128 v188, v[8:11]
	s_waitcnt vmcnt(3)
	ds_write_b128 v189, v[12:15]
	s_waitcnt vmcnt(2)
	ds_write_b128 v190, v[16:19]
	s_waitcnt vmcnt(1)
	ds_write_b128 v171, v[20:23]
	s_waitcnt vmcnt(0)
	ds_write_b128 v175, v[24:27]
	v_mov_b32_e32 v38, v40
	v_mov_b32_e32 v39, v40
	v_mov_b32_e32 v36, v40
	v_mov_b32_e32 v37, v40
	s_waitcnt lgkmcnt(0)
	s_barrier

.LBB0_151:
	s_ashr_i32 s0, s51, 1
	s_sub_i32 s0, s47, s0
	s_lshl_b32 s0, 1, s0
	s_and_b32 s1, s0, s49
	s_cmp_eq_u32 s1, 0
	s_cbranch_scc1 .LBB0_137
	s_mul_i32 s1, s15, 0x11000
	s_add_i32 s1, s1, 0
	v_add_u32_e32 v84, s1, v167
	v_add_u32_e32 v195, v84, v158
	v_add3_u32 v197, s1, v158, v167
	ds_read_b128 v[84:87], v195
	ds_read_b128 v[88:91], v195 offset:64
	ds_read_b128 v[92:95], v195 offset:128
	ds_read_b128 v[96:99], v195 offset:192
	ds_read_b128 v[100:103], v197 offset:4352
	ds_read_b128 v[104:107], v197 offset:4416
	ds_read_b128 v[108:111], v197 offset:4480
	ds_read_b128 v[198:201], v197 offset:4544
	s_waitcnt lgkmcnt(7)
	v_mfma_f32_16x16x32_bf16 v[84:87], v[84:87], v[36:39], 0
	s_waitcnt lgkmcnt(6)
	v_mfma_f32_16x16x32_bf16 v[84:87], v[88:91], v[40:43], v[84:87]
	s_waitcnt lgkmcnt(5)
	v_mfma_f32_16x16x32_bf16 v[84:87], v[92:95], v[44:47], v[84:87]
	s_waitcnt lgkmcnt(4)
	v_mfma_f32_16x16x32_bf16 v[112:115], v[96:99], v[48:51], v[84:87]
	s_nop 5
	ds_read_b128 v[84:87], v197 offset:8704
	ds_read_b128 v[88:91], v197 offset:8768
	ds_read_b128 v[92:95], v197 offset:8832
	ds_read_b128 v[96:99], v197 offset:8896
	s_waitcnt lgkmcnt(7)
	v_mfma_f32_16x16x32_bf16 v[100:103], v[100:103], v[36:39], 0
	s_waitcnt lgkmcnt(6)
	v_mfma_f32_16x16x32_bf16 v[100:103], v[104:107], v[40:43], v[100:103]
	s_waitcnt lgkmcnt(5)
	v_mfma_f32_16x16x32_bf16 v[100:103], v[108:111], v[44:47], v[100:103]
	s_waitcnt lgkmcnt(4)
	v_mfma_f32_16x16x32_bf16 v[108:111], v[198:201], v[48:51], v[100:103]
	s_nop 5
	ds_read_b128 v[100:103], v197 offset:13056
	ds_read_b128 v[198:201], v197 offset:13120
	ds_read_b128 v[202:205], v197 offset:13184
	ds_read_b128 v[206:209], v197 offset:13248
	s_waitcnt lgkmcnt(7)
	v_mfma_f32_16x16x32_bf16 v[84:87], v[84:87], v[36:39], 0
	s_waitcnt lgkmcnt(6)
	v_mfma_f32_16x16x32_bf16 v[84:87], v[88:91], v[40:43], v[84:87]
	s_waitcnt lgkmcnt(5)
	v_mfma_f32_16x16x32_bf16 v[84:87], v[92:95], v[44:47], v[84:87]
	s_waitcnt lgkmcnt(4)
	v_mfma_f32_16x16x32_bf16 v[104:107], v[96:99], v[48:51], v[84:87]
	s_nop 5
	ds_read_b128 v[84:87], v197 offset:17408
	ds_read_b128 v[88:91], v197 offset:17472
	ds_read_b128 v[92:95], v197 offset:17536
	ds_read_b128 v[96:99], v197 offset:17600
	s_waitcnt lgkmcnt(7)
	v_mfma_f32_16x16x32_bf16 v[100:103], v[100:103], v[36:39], 0
	s_waitcnt lgkmcnt(6)
	v_mfma_f32_16x16x32_bf16 v[100:103], v[198:201], v[40:43], v[100:103]
	s_waitcnt lgkmcnt(5)
	v_mfma_f32_16x16x32_bf16 v[100:103], v[202:205], v[44:47], v[100:103]
	s_waitcnt lgkmcnt(4)
	v_mfma_f32_16x16x32_bf16 v[100:103], v[206:209], v[48:51], v[100:103]
	ds_read_b128 v[198:201], v197 offset:21760
	ds_read_b128 v[202:205], v197 offset:21824
	ds_read_b128 v[206:209], v197 offset:21888
	ds_read_b128 v[230:233], v197 offset:21952
	s_waitcnt lgkmcnt(7)
	v_mfma_f32_16x16x32_bf16 v[84:87], v[84:87], v[36:39], 0
	s_waitcnt lgkmcnt(6)
	v_mfma_f32_16x16x32_bf16 v[84:87], v[88:91], v[40:43], v[84:87]
	s_waitcnt lgkmcnt(5)
	v_mfma_f32_16x16x32_bf16 v[84:87], v[92:95], v[44:47], v[84:87]
	s_waitcnt lgkmcnt(4)
	v_mfma_f32_16x16x32_bf16 v[96:99], v[96:99], v[48:51], v[84:87]
	s_nop 5
	ds_read_b128 v[84:87], v197 offset:26112
	ds_read_b128 v[88:91], v197 offset:26176
	ds_read_b128 v[234:237], v197 offset:26240
	ds_read_b128 v[238:241], v197 offset:26304
	s_waitcnt lgkmcnt(7)
	v_mfma_f32_16x16x32_bf16 v[92:95], v[198:201], v[36:39], 0
	s_waitcnt lgkmcnt(6)
	v_mfma_f32_16x16x32_bf16 v[92:95], v[202:205], v[40:43], v[92:95]
	s_waitcnt lgkmcnt(5)
	v_mfma_f32_16x16x32_bf16 v[92:95], v[206:209], v[44:47], v[92:95]
	s_waitcnt lgkmcnt(4)
	v_mfma_f32_16x16x32_bf16 v[92:95], v[230:233], v[48:51], v[92:95]
	ds_read_b128 v[198:201], v197 offset:30464
	ds_read_b128 v[202:205], v197 offset:30528
	ds_read_b128 v[206:209], v197 offset:30592
	ds_read_b128 v[230:233], v197 offset:30656
	s_waitcnt lgkmcnt(7)
	v_mfma_f32_16x16x32_bf16 v[84:87], v[84:87], v[36:39], 0
	s_waitcnt lgkmcnt(6)
	v_mfma_f32_16x16x32_bf16 v[84:87], v[88:91], v[40:43], v[84:87]
	s_waitcnt lgkmcnt(5)
	v_mfma_f32_16x16x32_bf16 v[84:87], v[234:237], v[44:47], v[84:87]
	s_waitcnt lgkmcnt(4)
	v_mfma_f32_16x16x32_bf16 v[88:91], v[238:241], v[48:51], v[84:87]
	s_waitcnt lgkmcnt(3)
	v_mfma_f32_16x16x32_bf16 v[84:87], v[198:201], v[36:39], 0
	s_waitcnt lgkmcnt(2)
	v_mfma_f32_16x16x32_bf16 v[84:87], v[202:205], v[40:43], v[84:87]
	s_waitcnt lgkmcnt(1)
	v_mfma_f32_16x16x32_bf16 v[84:87], v[206:209], v[44:47], v[84:87]
	s_waitcnt lgkmcnt(0)
	v_mfma_f32_16x16x32_bf16 v[84:87], v[230:233], v[48:51], v[84:87]
	v_and_b32_e32 v197, s0, v139
	v_cmp_eq_u32_e64 s[0:1], 0, v197
	s_cmp_lt_u32 s51, 2
	s_mov_b64 s[10:11], -1
	s_cbranch_scc1 .LBB0_154
	v_max3_f32 v197, v112, v113, v114
	v_max3_f32 v198, v96, v97, v98
	v_max3_f32 v197, v197, v115, v108
	v_max3_f32 v198, v198, v99, v92
	v_max3_f32 v197, v197, v109, v110
	v_max3_f32 v198, v198, v93, v94
	v_max3_f32 v197, v197, v111, v104
	v_max3_f32 v198, v198, v95, v88
	v_max3_f32 v197, v197, v105, v106
	v_max3_f32 v198, v198, v89, v90
	v_max3_f32 v197, v197, v107, v100
	v_max3_f32 v198, v198, v91, v84
	v_max3_f32 v197, v197, v101, v102
	v_max3_f32 v198, v198, v85, v86
	v_max_f32_e32 v197, v197, v103
	v_max_f32_e32 v198, v198, v87
	v_max_f32_e32 v197, v197, v198
	v_cndmask_b32_e64 v197, v197, v215, s[0:1]
	s_mov_b64 s[10:11], 0

.LBB0_156:
	v_mov_b32_e32 v198, v197
	s_nop 1
	v_permlane16_swap_b32_e32 v197, v198
	v_max_f32_e32 v197, v197, v198
	v_mov_b32_e32 v198, v197
	s_nop 1
	v_permlane32_swap_b32_e32 v197, v198
	v_max3_f32 v197, v196, v197, v198
	v_cmp_neq_f32_e32 vcc, s73, v197
	s_nop 1
	v_cndmask_b32_e32 v198, 0, v197, vcc
	v_sub_f32_e32 v196, v196, v198
	v_mul_f32_e32 v199, 0x3e0293ee, v196
	v_mul_f32_e32 v196, 0xbe0293ee, v198
	v_cndmask_b32_e64 v198, v196, v215, s[0:1]
	v_fmamk_f32 v112, v112, 0x3e0293ee, v198
	v_exp_f32_e32 v112, v112
	v_fmamk_f32 v113, v113, 0x3e0293ee, v198
	v_exp_f32_e32 v113, v113
	v_fmamk_f32 v114, v114, 0x3e0293ee, v198
	v_exp_f32_e32 v114, v114
	v_fmamk_f32 v115, v115, 0x3e0293ee, v198
	v_exp_f32_e32 v115, v115
	v_fmamk_f32 v108, v108, 0x3e0293ee, v198
	v_add_f32_e32 v196, 0, v112
	v_exp_f32_e32 v108, v108
	v_fmamk_f32 v109, v109, 0x3e0293ee, v198
	v_add_f32_e32 v196, v113, v196
	v_exp_f32_e32 v109, v109
	v_fmamk_f32 v110, v110, 0x3e0293ee, v198
	v_add_f32_e32 v196, v114, v196
	v_exp_f32_e32 v110, v110
	v_fmamk_f32 v111, v111, 0x3e0293ee, v198
	v_add_f32_e32 v196, v115, v196
	v_exp_f32_e32 v111, v111
	v_fmamk_f32 v104, v104, 0x3e0293ee, v198
	v_add_f32_e32 v196, v108, v196
	v_exp_f32_e32 v104, v104
	v_fmamk_f32 v105, v105, 0x3e0293ee, v198
	v_add_f32_e32 v196, v109, v196
	v_exp_f32_e32 v105, v105
	v_fmamk_f32 v106, v106, 0x3e0293ee, v198
	v_add_f32_e32 v196, v110, v196
	v_exp_f32_e32 v106, v106
	v_fmamk_f32 v107, v107, 0x3e0293ee, v198
	v_add_f32_e32 v196, v111, v196
	v_exp_f32_e32 v107, v107
	v_fmamk_f32 v100, v100, 0x3e0293ee, v198
	v_add_f32_e32 v196, v104, v196
	v_exp_f32_e32 v100, v100
	v_fmamk_f32 v101, v101, 0x3e0293ee, v198
	v_add_f32_e32 v196, v105, v196
	v_exp_f32_e32 v101, v101
	v_fmamk_f32 v102, v102, 0x3e0293ee, v198
	v_add_f32_e32 v196, v106, v196
	v_exp_f32_e32 v102, v102
	v_fmamk_f32 v103, v103, 0x3e0293ee, v198
	v_add_f32_e32 v196, v107, v196
	v_exp_f32_e32 v103, v103
	v_fmamk_f32 v96, v96, 0x3e0293ee, v198
	v_add_f32_e32 v196, v100, v196
	v_exp_f32_e32 v96, v96
	v_fmamk_f32 v97, v97, 0x3e0293ee, v198
	v_add_f32_e32 v196, v101, v196
	v_exp_f32_e32 v97, v97
	v_fmamk_f32 v98, v98, 0x3e0293ee, v198
	v_add_f32_e32 v196, v102, v196
	v_exp_f32_e32 v98, v98
	v_fmamk_f32 v99, v99, 0x3e0293ee, v198
	v_add_f32_e32 v196, v103, v196
	v_exp_f32_e32 v99, v99
	v_fmamk_f32 v92, v92, 0x3e0293ee, v198
	v_add_f32_e32 v196, v96, v196
	v_exp_f32_e32 v92, v92
	v_fmamk_f32 v93, v93, 0x3e0293ee, v198
	v_add_f32_e32 v196, v97, v196
	v_exp_f32_e32 v93, v93
	v_fmamk_f32 v94, v94, 0x3e0293ee, v198
	v_add_f32_e32 v196, v98, v196
	v_exp_f32_e32 v94, v94
	v_fmamk_f32 v95, v95, 0x3e0293ee, v198
	v_add_f32_e32 v196, v99, v196
	v_exp_f32_e32 v95, v95
	v_fmamk_f32 v88, v88, 0x3e0293ee, v198
	v_add_f32_e32 v196, v92, v196
	v_exp_f32_e32 v88, v88
	v_fmamk_f32 v89, v89, 0x3e0293ee, v198
	v_add_f32_e32 v196, v93, v196
	v_exp_f32_e32 v89, v89
	v_fmamk_f32 v90, v90, 0x3e0293ee, v198
	v_add_f32_e32 v196, v94, v196
	v_exp_f32_e32 v90, v90
	v_fmamk_f32 v91, v91, 0x3e0293ee, v198
	v_add_f32_e32 v196, v95, v196
	v_exp_f32_e32 v91, v91
	v_add_f32_e32 v196, v88, v196
	v_add_f32_e32 v196, v89, v196
	v_add_f32_e32 v196, v90, v196
	v_fmamk_f32 v84, v84, 0x3e0293ee, v198
	v_add_f32_e32 v200, v91, v196
	v_exp_f32_e32 v196, v84
	v_fmamk_f32 v85, v85, 0x3e0293ee, v198
	v_exp_f32_e32 v85, v85
	v_fmamk_f32 v86, v86, 0x3e0293ee, v198
	v_exp_f32_e32 v86, v86
	v_fmac_f32_e32 v198, 0x3e0293ee, v87
	v_exp_f32_e32 v87, v198
	v_add_f32_e32 v84, v196, v200
	v_add_f32_e32 v84, v85, v84
	v_add_f32_e32 v84, v86, v84
	v_add_f32_e32 v198, v87, v84
	v_exp_f32_e32 v84, v199
	v_mov_b32_e32 v199, v198
	s_nop 1
	v_permlane16_swap_b32_e32 v198, v199
	v_add_f32_e32 v198, v198, v199
	v_mov_b32_e32 v199, v198
	v_cmp_neq_f32_e32 vcc, 1.0, v84
	s_nop 0
	v_permlane32_swap_b32_e32 v198, v199
	s_cbranch_vccz .LBB0_158
	v_pk_mul_f32 v[82:83], v[82:83], v[84:85] op_sel_hi:[1,0]
	v_pk_mul_f32 v[80:81], v[80:81], v[84:85] op_sel_hi:[1,0]
	v_pk_mul_f32 v[78:79], v[78:79], v[84:85] op_sel_hi:[1,0]
	v_pk_mul_f32 v[76:77], v[76:77], v[84:85] op_sel_hi:[1,0]
	v_pk_mul_f32 v[74:75], v[74:75], v[84:85] op_sel_hi:[1,0]
	v_pk_mul_f32 v[72:73], v[72:73], v[84:85] op_sel_hi:[1,0]
	v_pk_mul_f32 v[70:71], v[70:71], v[84:85] op_sel_hi:[1,0]
	v_pk_mul_f32 v[68:69], v[68:69], v[84:85] op_sel_hi:[1,0]
	v_pk_mul_f32 v[66:67], v[66:67], v[84:85] op_sel_hi:[1,0]
	v_pk_mul_f32 v[64:65], v[64:65], v[84:85] op_sel_hi:[1,0]
	v_pk_mul_f32 v[62:63], v[62:63], v[84:85] op_sel_hi:[1,0]
	v_pk_mul_f32 v[60:61], v[60:61], v[84:85] op_sel_hi:[1,0]
	v_pk_mul_f32 v[58:59], v[58:59], v[84:85] op_sel_hi:[1,0]
	v_pk_mul_f32 v[56:57], v[56:57], v[84:85] op_sel_hi:[1,0]
	v_pk_mul_f32 v[54:55], v[54:55], v[84:85] op_sel_hi:[1,0]
	v_pk_mul_f32 v[52:53], v[52:53], v[84:85] op_sel_hi:[1,0]
